# gemm1 epilogue: hoisted the 4 loop-invariant qk_g float4 loads out of the 8 (ai,m) blocks (32 load+vmcnt(0) store-drains per tile removed)
# speedup vs baseline: 1.0610x; 1.0060x over previous
; __device__ __forceinline__ float xor16(float v) { return __int_as_float(__builtin_amdgcn_ds_swizzle(__float_as_int(v), 0x401F)); }
;   __device__ __forceinline__ void operator()(const f32x4 (&acc)[2][2][4][2], const g8::Unit& u, int ui, int wr, int wc, int fr, int fq) const {
;     const int hs = u.pn * 4 + wc;
;     int gi = -1;
;     if (hs < 4) gi = 0; else if (hs < 6) gi = 1; else if (hs >= 16 && hs < 20) gi = 2; else if (hs == 22) gi = 4; else if (hs == 24) gi = 5;
;     const bool gate = (hs == 26);
; #pragma unroll
;     for (int ai = 0; ai < 2; ++ai)
; #pragma unroll
;       for (int m = 0; m < 4; ++m) {
;         const int rl = 128 * ai + 64 * wr + 16 * m + fr;
;         float r = rsl[ui * 256 + rl];
;         if (gi >= 0) {
;           float ss = 0.f;
; #pragma unroll
;           for (int bj = 0; bj < 2; ++bj)
; #pragma unroll
;             for (int n = 0; n < 2; ++n)
; #pragma unroll
;               for (int j = 0; j < 4; ++j) ss += acc[ai][bj][m][n][j] * acc[ai][bj][m][n][j];
;           ss += xor16(ss);
;           ss += __shfl_xor(ss, 32);
;           r *= rsqrtf(ss * r * r * (1.f / 64.f) + EPS);
.LBB0_210:
	s_lshl_b32 s3, s3, 10
	v_add_u32_e32 v177, s3, v160
	s_and_b64 vcc, exec, s[26:27]
	s_cbranch_vccz .Lg1_nopre
	v_lshl_add_u64 v[218:219], s[12:13], 2, v[134:135]
	global_load_dwordx4 v[202:205], v[218:219], off
	global_load_dwordx4 v[206:209], v[218:219], off offset:16
	global_load_dwordx4 v[210:213], v[218:219], off offset:128
	global_load_dwordx4 v[214:217], v[218:219], off offset:144
.Lg1_nopre:
	s_waitcnt vmcnt(0)
	ds_read_b32 v140, v177
	s_xor_b64 s[14:15], s[26:27], -1
	s_and_b64 vcc, exec, s[14:15]
	s_cbranch_vccnz .LBB0_212
	v_mul_f32_e32 v141, v127, v127
	v_fmac_f32_e32 v141, v126, v126
	v_fmac_f32_e32 v141, v128, v128
	v_fmac_f32_e32 v141, v129, v129
	v_fmac_f32_e32 v141, v122, v122
	v_fmac_f32_e32 v141, v123, v123
	v_fmac_f32_e32 v141, v124, v124
	v_fmac_f32_e32 v141, v125, v125
	v_fmac_f32_e32 v141, v118, v118
	v_fmac_f32_e32 v141, v119, v119
	v_pk_mul_f32 v[152:153], v[120:121], v[120:121]
	v_pk_mul_f32 v[154:155], v[114:115], v[114:115]
	v_add_f32_e32 v141, v152, v141
	v_add_f32_e32 v141, v153, v141
	v_add_f32_e32 v141, v154, v141
	v_pk_mul_f32 v[152:153], v[116:117], v[116:117]
	v_add_f32_e32 v141, v155, v141
	v_add_f32_e32 v141, v152, v141
	v_add_f32_e32 v141, v153, v141
	ds_swizzle_b32 v152, v141 offset:swizzle(SWAP,16)
	v_xor_b32_e32 v153, 32, v199
	s_waitcnt lgkmcnt(0)
	v_add_f32_e32 v141, v141, v152
	v_and_b32_e32 v152, 64, v199
	v_add_u32_e32 v152, 64, v152
	v_cmp_lt_i32_e32 vcc, v153, v152
	s_nop 1
	v_cndmask_b32_e32 v152, v199, v153, vcc
	v_lshlrev_b32_e32 v152, 2, v152
	ds_bpermute_b32 v152, v152, v141
	s_waitcnt lgkmcnt(0)
	v_add_f32_e32 v141, v141, v152
	v_mul_f32_e32 v141, v140, v141
	v_mul_f32_e32 v141, v140, v141
	v_fmamk_f32 v141, v141, 0x3c800000, v144
	v_mul_f32_e32 v152, 0x4b800000, v141
	v_cmp_gt_f32_e32 vcc, s75, v141
	s_nop 1
	v_cndmask_b32_e32 v141, v141, v152, vcc
	v_rsq_f32_e32 v141, v141
	s_nop 0
	v_mul_f32_e32 v152, 0x45800000, v141
	v_cndmask_b32_e32 v141, v141, v152, vcc
	v_mul_f32_e32 v140, v140, v141

;   __device__ __forceinline__ void operator()(const f32x4 (&acc)[2][2][4][2], const g8::Unit& u, int ui, int wr, int wc, int fr, int fq) const {
;     ...
;             v[n] = acc[ai][bj][m][n] * r;
;             if (gi >= 0) {
;               const float4 g4 = *(const float4*)(qkg + gi * 64 + 32 * bj + 8 * fq + 4 * n);
;               v[n][0] *= g4.x; v[n][1] *= g4.y; v[n][2] *= g4.z; v[n][3] *= g4.w;
.LBB0_224:
	s_nop 1
	v_pk_mul_f32 v[128:129], v[156:157], v[202:203]
	v_pk_mul_f32 v[152:153], v[154:155], v[204:205]

;   __device__ __forceinline__ void operator()(const f32x4 (&acc)[2][2][4][2], const g8::Unit& u, int ui, int wr, int wc, int fr, int fq) const {
;     ...
;             v[n] = acc[ai][bj][m][n] * r;
;             if (gi >= 0) {
;               const float4 g4 = *(const float4*)(qkg + gi * 64 + 32 * bj + 8 * fq + 4 * n);
;               v[n][0] *= g4.x; v[n][1] *= g4.y; v[n][2] *= g4.z; v[n][3] *= g4.w;
.LBB0_239:
	s_andn2_b64 vcc, exec, s[14:15]
	s_cbranch_vccnz .LBB0_241
	s_nop 1
	v_pk_mul_f32 v[154:155], v[122:123], v[206:207]
	v_pk_mul_f32 v[156:157], v[124:125], v[208:209]

;   __device__ __forceinline__ void operator()(const f32x4 (&acc)[2][2][4][2], const g8::Unit& u, int ui, int wr, int wc, int fr, int fq) const {
;     ...
;             v[n] = acc[ai][bj][m][n] * r;
;             if (gi >= 0) {
;               const float4 g4 = *(const float4*)(qkg + gi * 64 + 32 * bj + 8 * fq + 4 * n);
;               v[n][0] *= g4.x; v[n][1] *= g4.y; v[n][2] *= g4.z; v[n][3] *= g4.w;
.LBB0_245:
	s_nop 1
	v_pk_mul_f32 v[120:121], v[128:129], v[210:211]
	v_pk_mul_f32 v[118:119], v[124:125], v[212:213]

;   __device__ __forceinline__ void operator()(const f32x4 (&acc)[2][2][4][2], const g8::Unit& u, int ui, int wr, int wc, int fr, int fq) const {
;     ...
;             v[n] = acc[ai][bj][m][n] * r;
;             if (gi >= 0) {
;               const float4 g4 = *(const float4*)(qkg + gi * 64 + 32 * bj + 8 * fq + 4 * n);
;               v[n][0] *= g4.x; v[n][1] *= g4.y; v[n][2] *= g4.z; v[n][3] *= g4.w;
.LBB0_250:
	s_nop 1
	v_pk_mul_f32 v[128:129], v[114:115], v[214:215]
	v_pk_mul_f32 v[124:125], v[116:117], v[216:217]

;   __device__ __forceinline__ void operator()(const f32x4 (&acc)[2][2][4][2], const g8::Unit& u, int ui, int wr, int wc, int fr, int fq) const {
;     ...
;             v[n] = acc[ai][bj][m][n] * r;
;             if (gi >= 0) {
;               const float4 g4 = *(const float4*)(qkg + gi * 64 + 32 * bj + 8 * fq + 4 * n);
;               v[n][0] *= g4.x; v[n][1] *= g4.y; v[n][2] *= g4.z; v[n][3] *= g4.w;
.LBB0_268:
	s_andn2_b64 vcc, exec, s[26:27]
	s_cbranch_vccnz .LBB0_270
	s_nop 1
	v_pk_mul_f32 v[110:111], v[118:119], v[202:203]
	v_pk_mul_f32 v[112:113], v[116:117], v[204:205]

;   __device__ __forceinline__ void operator()(const f32x4 (&acc)[2][2][4][2], const g8::Unit& u, int ui, int wr, int wc, int fr, int fq) const {
;     ...
;             v[n] = acc[ai][bj][m][n] * r;
;             if (gi >= 0) {
;               const float4 g4 = *(const float4*)(qkg + gi * 64 + 32 * bj + 8 * fq + 4 * n);
;               v[n][0] *= g4.x; v[n][1] *= g4.y; v[n][2] *= g4.z; v[n][3] *= g4.w;
.LBB0_283:
	s_andn2_b64 vcc, exec, s[26:27]
	s_cbranch_vccnz .LBB0_285
	s_nop 1
	v_pk_mul_f32 v[116:117], v[106:107], v[206:207]
	v_pk_mul_f32 v[118:119], v[108:109], v[208:209]

;   __device__ __forceinline__ void operator()(const f32x4 (&acc)[2][2][4][2], const g8::Unit& u, int ui, int wr, int wc, int fr, int fq) const {
;     ...
;             v[n] = acc[ai][bj][m][n] * r;
;             if (gi >= 0) {
;               const float4 g4 = *(const float4*)(qkg + gi * 64 + 32 * bj + 8 * fq + 4 * n);
;               v[n][0] *= g4.x; v[n][1] *= g4.y; v[n][2] *= g4.z; v[n][3] *= g4.w;
.LBB0_289:
	s_nop 1
	v_pk_mul_f32 v[104:105], v[110:111], v[210:211]
	v_pk_mul_f32 v[102:103], v[108:109], v[212:213]

;   __device__ __forceinline__ void operator()(const f32x4 (&acc)[2][2][4][2], const g8::Unit& u, int ui, int wr, int wc, int fr, int fq) const {
;     ...
;             v[n] = acc[ai][bj][m][n] * r;
;             if (gi >= 0) {
;               const float4 g4 = *(const float4*)(qkg + gi * 64 + 32 * bj + 8 * fq + 4 * n);
;               v[n][0] *= g4.x; v[n][1] *= g4.y; v[n][2] *= g4.z; v[n][3] *= g4.w;
.LBB0_294:
	s_nop 1
	v_pk_mul_f32 v[110:111], v[98:99], v[214:215]
	v_pk_mul_f32 v[108:109], v[100:101], v[216:217]

;   __device__ __forceinline__ void operator()(const f32x4 (&acc)[2][2][4][2], const g8::Unit& u, int ui, int wr, int wc, int fr, int fq) const {
;     ...
;             v[n] = acc[ai][bj][m][n] * r;
;             if (gi >= 0) {
;               const float4 g4 = *(const float4*)(qkg + gi * 64 + 32 * bj + 8 * fq + 4 * n);
;               v[n][0] *= g4.x; v[n][1] *= g4.y; v[n][2] *= g4.z; v[n][3] *= g4.w;
.LBB0_312:
	s_andn2_b64 vcc, exec, s[26:27]
	s_cbranch_vccnz .LBB0_314
	s_nop 1
	v_pk_mul_f32 v[94:95], v[102:103], v[202:203]
	v_pk_mul_f32 v[96:97], v[100:101], v[204:205]

;   __device__ __forceinline__ void operator()(const f32x4 (&acc)[2][2][4][2], const g8::Unit& u, int ui, int wr, int wc, int fr, int fq) const {
;     ...
;             v[n] = acc[ai][bj][m][n] * r;
;             if (gi >= 0) {
;               const float4 g4 = *(const float4*)(qkg + gi * 64 + 32 * bj + 8 * fq + 4 * n);
;               v[n][0] *= g4.x; v[n][1] *= g4.y; v[n][2] *= g4.z; v[n][3] *= g4.w;
.LBB0_327:
	s_andn2_b64 vcc, exec, s[26:27]
	s_cbranch_vccnz .LBB0_329
	s_nop 1
	v_pk_mul_f32 v[100:101], v[90:91], v[206:207]
	v_pk_mul_f32 v[102:103], v[92:93], v[208:209]

;   __device__ __forceinline__ void operator()(const f32x4 (&acc)[2][2][4][2], const g8::Unit& u, int ui, int wr, int wc, int fr, int fq) const {
;     ...
;             v[n] = acc[ai][bj][m][n] * r;
;             if (gi >= 0) {
;               const float4 g4 = *(const float4*)(qkg + gi * 64 + 32 * bj + 8 * fq + 4 * n);
;               v[n][0] *= g4.x; v[n][1] *= g4.y; v[n][2] *= g4.z; v[n][3] *= g4.w;
.LBB0_333:
	s_nop 1
	v_pk_mul_f32 v[88:89], v[94:95], v[210:211]
	v_pk_mul_f32 v[86:87], v[92:93], v[212:213]

;   __device__ __forceinline__ void operator()(const f32x4 (&acc)[2][2][4][2], const g8::Unit& u, int ui, int wr, int wc, int fr, int fq) const {
;     ...
;             v[n] = acc[ai][bj][m][n] * r;
;             if (gi >= 0) {
;               const float4 g4 = *(const float4*)(qkg + gi * 64 + 32 * bj + 8 * fq + 4 * n);
;               v[n][0] *= g4.x; v[n][1] *= g4.y; v[n][2] *= g4.z; v[n][3] *= g4.w;
.LBB0_338:
	s_nop 1
	v_pk_mul_f32 v[94:95], v[82:83], v[214:215]
	v_pk_mul_f32 v[92:93], v[84:85], v[216:217]

;   __device__ __forceinline__ void operator()(const f32x4 (&acc)[2][2][4][2], const g8::Unit& u, int ui, int wr, int wc, int fr, int fq) const {
;     ...
;             v[n] = acc[ai][bj][m][n] * r;
;             if (gi >= 0) {
;               const float4 g4 = *(const float4*)(qkg + gi * 64 + 32 * bj + 8 * fq + 4 * n);
;               v[n][0] *= g4.x; v[n][1] *= g4.y; v[n][2] *= g4.z; v[n][3] *= g4.w;
.LBB0_356:
	s_andn2_b64 vcc, exec, s[26:27]
	s_cbranch_vccnz .LBB0_358
	s_nop 1
	v_pk_mul_f32 v[78:79], v[86:87], v[202:203]
	v_pk_mul_f32 v[80:81], v[84:85], v[204:205]

;   __device__ __forceinline__ void operator()(const f32x4 (&acc)[2][2][4][2], const g8::Unit& u, int ui, int wr, int wc, int fr, int fq) const {
;     ...
;             v[n] = acc[ai][bj][m][n] * r;
;             if (gi >= 0) {
;               const float4 g4 = *(const float4*)(qkg + gi * 64 + 32 * bj + 8 * fq + 4 * n);
;               v[n][0] *= g4.x; v[n][1] *= g4.y; v[n][2] *= g4.z; v[n][3] *= g4.w;
.LBB0_371:
	s_andn2_b64 vcc, exec, s[26:27]
	s_cbranch_vccnz .LBB0_373
	s_nop 1
	v_pk_mul_f32 v[84:85], v[74:75], v[206:207]
	v_pk_mul_f32 v[86:87], v[76:77], v[208:209]

;   __device__ __forceinline__ void operator()(const f32x4 (&acc)[2][2][4][2], const g8::Unit& u, int ui, int wr, int wc, int fr, int fq) const {
;     ...
;             v[n] = acc[ai][bj][m][n] * r;
;             if (gi >= 0) {
;               const float4 g4 = *(const float4*)(qkg + gi * 64 + 32 * bj + 8 * fq + 4 * n);
;               v[n][0] *= g4.x; v[n][1] *= g4.y; v[n][2] *= g4.z; v[n][3] *= g4.w;
.LBB0_377:
	s_nop 1
	v_pk_mul_f32 v[72:73], v[78:79], v[210:211]
	v_pk_mul_f32 v[70:71], v[76:77], v[212:213]

;   __device__ __forceinline__ void operator()(const f32x4 (&acc)[2][2][4][2], const g8::Unit& u, int ui, int wr, int wc, int fr, int fq) const {
;     ...
;             v[n] = acc[ai][bj][m][n] * r;
;             if (gi >= 0) {
;               const float4 g4 = *(const float4*)(qkg + gi * 64 + 32 * bj + 8 * fq + 4 * n);
;               v[n][0] *= g4.x; v[n][1] *= g4.y; v[n][2] *= g4.z; v[n][3] *= g4.w;
.LBB0_382:
	s_nop 1
	v_pk_mul_f32 v[78:79], v[66:67], v[214:215]
	v_pk_mul_f32 v[76:77], v[68:69], v[216:217]

;   __device__ __forceinline__ void operator()(const f32x4 (&acc)[2][2][4][2], const g8::Unit& u, int ui, int wr, int wc, int fr, int fq) const {
;     ...
;             v[n] = acc[ai][bj][m][n] * r;
;             if (gi >= 0) {
;               const float4 g4 = *(const float4*)(qkg + gi * 64 + 32 * bj + 8 * fq + 4 * n);
;               v[n][0] *= g4.x; v[n][1] *= g4.y; v[n][2] *= g4.z; v[n][3] *= g4.w;
.LBB0_400:
	s_andn2_b64 vcc, exec, s[26:27]
	s_cbranch_vccnz .LBB0_402
	s_nop 1
	v_pk_mul_f32 v[62:63], v[70:71], v[202:203]
	v_pk_mul_f32 v[64:65], v[68:69], v[204:205]

;   __device__ __forceinline__ void operator()(const f32x4 (&acc)[2][2][4][2], const g8::Unit& u, int ui, int wr, int wc, int fr, int fq) const {
;     ...
;             v[n] = acc[ai][bj][m][n] * r;
;             if (gi >= 0) {
;               const float4 g4 = *(const float4*)(qkg + gi * 64 + 32 * bj + 8 * fq + 4 * n);
;               v[n][0] *= g4.x; v[n][1] *= g4.y; v[n][2] *= g4.z; v[n][3] *= g4.w;
.LBB0_415:
	s_andn2_b64 vcc, exec, s[26:27]
	s_cbranch_vccnz .LBB0_417
	s_nop 1
	v_pk_mul_f32 v[68:69], v[58:59], v[206:207]
	v_pk_mul_f32 v[70:71], v[60:61], v[208:209]

;   __device__ __forceinline__ void operator()(const f32x4 (&acc)[2][2][4][2], const g8::Unit& u, int ui, int wr, int wc, int fr, int fq) const {
;     ...
;             v[n] = acc[ai][bj][m][n] * r;
;             if (gi >= 0) {
;               const float4 g4 = *(const float4*)(qkg + gi * 64 + 32 * bj + 8 * fq + 4 * n);
;               v[n][0] *= g4.x; v[n][1] *= g4.y; v[n][2] *= g4.z; v[n][3] *= g4.w;
.LBB0_421:
	s_nop 1
	v_pk_mul_f32 v[56:57], v[62:63], v[210:211]
	v_pk_mul_f32 v[54:55], v[60:61], v[212:213]

;   __device__ __forceinline__ void operator()(const f32x4 (&acc)[2][2][4][2], const g8::Unit& u, int ui, int wr, int wc, int fr, int fq) const {
;     ...
;             v[n] = acc[ai][bj][m][n] * r;
;             if (gi >= 0) {
;               const float4 g4 = *(const float4*)(qkg + gi * 64 + 32 * bj + 8 * fq + 4 * n);
;               v[n][0] *= g4.x; v[n][1] *= g4.y; v[n][2] *= g4.z; v[n][3] *= g4.w;
.LBB0_426:
	s_nop 1
	v_pk_mul_f32 v[62:63], v[50:51], v[214:215]
	v_pk_mul_f32 v[60:61], v[52:53], v[216:217]

;   __device__ __forceinline__ void operator()(const f32x4 (&acc)[2][2][4][2], const g8::Unit& u, int ui, int wr, int wc, int fr, int fq) const {
;     ...
;             v[n] = acc[ai][bj][m][n] * r;
;             if (gi >= 0) {
;               const float4 g4 = *(const float4*)(qkg + gi * 64 + 32 * bj + 8 * fq + 4 * n);
;               v[n][0] *= g4.x; v[n][1] *= g4.y; v[n][2] *= g4.z; v[n][3] *= g4.w;
.LBB0_444:
	s_andn2_b64 vcc, exec, s[26:27]
	s_cbranch_vccnz .LBB0_446
	s_nop 1
	v_pk_mul_f32 v[46:47], v[54:55], v[202:203]
	v_pk_mul_f32 v[48:49], v[52:53], v[204:205]

;   __device__ __forceinline__ void operator()(const f32x4 (&acc)[2][2][4][2], const g8::Unit& u, int ui, int wr, int wc, int fr, int fq) const {
;     ...
;             v[n] = acc[ai][bj][m][n] * r;
;             if (gi >= 0) {
;               const float4 g4 = *(const float4*)(qkg + gi * 64 + 32 * bj + 8 * fq + 4 * n);
;               v[n][0] *= g4.x; v[n][1] *= g4.y; v[n][2] *= g4.z; v[n][3] *= g4.w;
.LBB0_459:
	s_andn2_b64 vcc, exec, s[26:27]
	s_cbranch_vccnz .LBB0_461
	s_nop 1
	v_pk_mul_f32 v[52:53], v[42:43], v[206:207]
	v_pk_mul_f32 v[54:55], v[44:45], v[208:209]

;   __device__ __forceinline__ void operator()(const f32x4 (&acc)[2][2][4][2], const g8::Unit& u, int ui, int wr, int wc, int fr, int fq) const {
;     ...
;             v[n] = acc[ai][bj][m][n] * r;
;             if (gi >= 0) {
;               const float4 g4 = *(const float4*)(qkg + gi * 64 + 32 * bj + 8 * fq + 4 * n);
;               v[n][0] *= g4.x; v[n][1] *= g4.y; v[n][2] *= g4.z; v[n][3] *= g4.w;
.LBB0_465:
	s_nop 1
	v_pk_mul_f32 v[40:41], v[46:47], v[210:211]
	v_pk_mul_f32 v[38:39], v[44:45], v[212:213]

;   __device__ __forceinline__ void operator()(const f32x4 (&acc)[2][2][4][2], const g8::Unit& u, int ui, int wr, int wc, int fr, int fq) const {
;     ...
;             v[n] = acc[ai][bj][m][n] * r;
;             if (gi >= 0) {
;               const float4 g4 = *(const float4*)(qkg + gi * 64 + 32 * bj + 8 * fq + 4 * n);
;               v[n][0] *= g4.x; v[n][1] *= g4.y; v[n][2] *= g4.z; v[n][3] *= g4.w;
.LBB0_470:
	s_nop 1
	v_pk_mul_f32 v[46:47], v[34:35], v[214:215]
	v_pk_mul_f32 v[44:45], v[36:37], v[216:217]

;   __device__ __forceinline__ void operator()(const f32x4 (&acc)[2][2][4][2], const g8::Unit& u, int ui, int wr, int wc, int fr, int fq) const {
;     ...
;             v[n] = acc[ai][bj][m][n] * r;
;             if (gi >= 0) {
;               const float4 g4 = *(const float4*)(qkg + gi * 64 + 32 * bj + 8 * fq + 4 * n);
;               v[n][0] *= g4.x; v[n][1] *= g4.y; v[n][2] *= g4.z; v[n][3] *= g4.w;
.LBB0_488:
	s_andn2_b64 vcc, exec, s[26:27]
	s_cbranch_vccnz .LBB0_490
	s_nop 1
	v_pk_mul_f32 v[30:31], v[38:39], v[202:203]
	v_pk_mul_f32 v[32:33], v[36:37], v[204:205]

;   __device__ __forceinline__ void operator()(const f32x4 (&acc)[2][2][4][2], const g8::Unit& u, int ui, int wr, int wc, int fr, int fq) const {
;     ...
;             v[n] = acc[ai][bj][m][n] * r;
;             if (gi >= 0) {
;               const float4 g4 = *(const float4*)(qkg + gi * 64 + 32 * bj + 8 * fq + 4 * n);
;               v[n][0] *= g4.x; v[n][1] *= g4.y; v[n][2] *= g4.z; v[n][3] *= g4.w;
.LBB0_503:
	s_andn2_b64 vcc, exec, s[26:27]
	s_cbranch_vccnz .LBB0_505
	s_nop 1
	v_pk_mul_f32 v[36:37], v[26:27], v[206:207]
	v_pk_mul_f32 v[38:39], v[28:29], v[208:209]

;   __device__ __forceinline__ void operator()(const f32x4 (&acc)[2][2][4][2], const g8::Unit& u, int ui, int wr, int wc, int fr, int fq) const {
;     ...
;             v[n] = acc[ai][bj][m][n] * r;
;             if (gi >= 0) {
;               const float4 g4 = *(const float4*)(qkg + gi * 64 + 32 * bj + 8 * fq + 4 * n);
;               v[n][0] *= g4.x; v[n][1] *= g4.y; v[n][2] *= g4.z; v[n][3] *= g4.w;
.LBB0_509:
	s_nop 1
	v_pk_mul_f32 v[24:25], v[30:31], v[210:211]
	v_pk_mul_f32 v[22:23], v[28:29], v[212:213]

;   __device__ __forceinline__ void operator()(const f32x4 (&acc)[2][2][4][2], const g8::Unit& u, int ui, int wr, int wc, int fr, int fq) const {
;     ...
;             v[n] = acc[ai][bj][m][n] * r;
;             if (gi >= 0) {
;               const float4 g4 = *(const float4*)(qkg + gi * 64 + 32 * bj + 8 * fq + 4 * n);
;               v[n][0] *= g4.x; v[n][1] *= g4.y; v[n][2] *= g4.z; v[n][3] *= g4.w;
.LBB0_514:
	s_nop 1
	v_pk_mul_f32 v[30:31], v[18:19], v[214:215]
	v_pk_mul_f32 v[28:29], v[20:21], v[216:217]

;   __device__ __forceinline__ void operator()(const f32x4 (&acc)[2][2][4][2], const g8::Unit& u, int ui, int wr, int wc, int fr, int fq) const {
;     ...
;             v[n] = acc[ai][bj][m][n] * r;
;             if (gi >= 0) {
;               const float4 g4 = *(const float4*)(qkg + gi * 64 + 32 * bj + 8 * fq + 4 * n);
;               v[n][0] *= g4.x; v[n][1] *= g4.y; v[n][2] *= g4.z; v[n][3] *= g4.w;
.LBB0_532:
	s_andn2_b64 vcc, exec, s[14:15]
	s_cbranch_vccnz .LBB0_534
	s_nop 1
	v_pk_mul_f32 v[14:15], v[22:23], v[202:203]
	v_pk_mul_f32 v[16:17], v[20:21], v[204:205]

;   __device__ __forceinline__ void operator()(const f32x4 (&acc)[2][2][4][2], const g8::Unit& u, int ui, int wr, int wc, int fr, int fq) const {
;     ...
;             v[n] = acc[ai][bj][m][n] * r;
;             if (gi >= 0) {
;               const float4 g4 = *(const float4*)(qkg + gi * 64 + 32 * bj + 8 * fq + 4 * n);
;               v[n][0] *= g4.x; v[n][1] *= g4.y; v[n][2] *= g4.z; v[n][3] *= g4.w;
.LBB0_547:
	s_andn2_b64 vcc, exec, s[14:15]
	s_cbranch_vccnz .LBB0_549
	s_nop 1
	v_pk_mul_f32 v[20:21], v[10:11], v[206:207]
	v_pk_mul_f32 v[22:23], v[12:13], v[208:209]

;   __device__ __forceinline__ void operator()(const f32x4 (&acc)[2][2][4][2], const g8::Unit& u, int ui, int wr, int wc, int fr, int fq) const {
;     ...
;             v[n] = acc[ai][bj][m][n] * r;
;             if (gi >= 0) {
;               const float4 g4 = *(const float4*)(qkg + gi * 64 + 32 * bj + 8 * fq + 4 * n);
;               v[n][0] *= g4.x; v[n][1] *= g4.y; v[n][2] *= g4.z; v[n][3] *= g4.w;
.LBB0_553:
	s_nop 1
	v_pk_mul_f32 v[8:9], v[14:15], v[210:211]
	v_pk_mul_f32 v[6:7], v[12:13], v[212:213]

;   __device__ __forceinline__ void operator()(const f32x4 (&acc)[2][2][4][2], const g8::Unit& u, int ui, int wr, int wc, int fr, int fq) const {
;     ...
;             v[n] = acc[ai][bj][m][n] * r;
;             if (gi >= 0) {
;               const float4 g4 = *(const float4*)(qkg + gi * 64 + 32 * bj + 8 * fq + 4 * n);
;               v[n][0] *= g4.x; v[n][1] *= g4.y; v[n][2] *= g4.z; v[n][3] *= g4.w;
.LBB0_558:
	s_nop 1
	v_pk_mul_f32 v[14:15], v[2:3], v[214:215]
	v_pk_mul_f32 v[12:13], v[4:5], v[216:217]
	s_branch .LBB0_191
